# ph4 out-proj epilogue: residual (bf16 X) pieces prefetched 5 steps ahead into spare VGPRs instead of load-wait per step (on top of v049)
# baseline (speedup 1.0000x reference)
.LBB0_232:
	s_mul_i32 s0, s58, 0x12000
	s_add_u32 s2, s18, s0
	v_readlane_b32 s20, v254, 3
	s_addc_u32 s3, s19, 0
	s_lshl_b32 s0, s11, 5
	v_readlane_b32 s22, v254, 5
	v_readlane_b32 s23, v254, 6
	s_add_u32 s1, s22, 0
	s_addc_u32 s18, s23, s46
	v_readlane_b32 s21, v254, 4
	s_add_u32 s20, s1, s45
	s_addc_u32 s21, s18, 0
	s_add_u32 s1, s22, 0
	s_addc_u32 s18, s23, s48
	s_add_u32 s22, s1, s47
	s_addc_u32 s23, s18, 0
	s_lshl_b32 s1, s14, 8
	s_lshl_b32 s28, s10, 8
	s_or_b32 s0, s1, s0
	v_lshrrev_b32_e32 v90, 2, v227
	v_and_or_b32 v204, v90, 12, s0
	s_add_i32 s0, s28, 0xffffe000
	s_lshr_b32 s0, s0, 12
	s_mulk_i32 s0, 0x1800
	s_add_i32 s24, s28, s38
	s_addk_i32 s0, 0x1800
	s_cmp_gt_i32 s10, 31
	s_cselect_b32 s60, s0, 0
	s_lshl_b64 s[0:1], s[60:61], 2
	s_add_u32 s0, s2, s0
	s_addc_u32 s1, s3, s1
	s_add_u32 s18, s0, 0x100000
	s_addc_u32 s19, s1, 0
	v_ashrrev_i32_e32 v205, 31, v204
	v_lshl_add_u64 v[90:91], v[204:205], 2, s[18:19]
	s_mov_b64 s[0:1], 0x2000
	v_lshl_add_u64 v[92:93], v[90:91], 0, s[0:1]
	s_movk_i32 s0, 0x2000
	v_add_co_u32_e32 v90, vcc, s0, v90
	s_barrier
	s_nop 0
	v_addc_co_u32_e32 v91, vcc, 0, v91, vcc
	global_load_dwordx4 v[106:109], v[92:93], off offset:64
	global_load_dwordx4 v[94:97], v[92:93], off offset:512
	global_load_dwordx4 v[110:113], v[90:91], off
	s_nop 0
	global_load_dwordx4 v[90:93], v[92:93], off offset:576
	v_or_b32_e32 v160, s24, v1
	v_ashrrev_i32_e32 v161, 31, v160
	v_lshlrev_b64 v[170:171], 10, v[160:161]
	s_cmp_lg_u64 s[16:17], 0
	v_cmp_gt_i32_e64 s[2:3], s0, v160
	s_cselect_b64 s[26:27], -1, 0
	s_cmp_eq_u64 s[16:17], 0
	v_lshl_add_u64 v[164:165], v[170:171], 1, s[16:17]
	s_mov_b32 s29, 0xf800000
	s_cbranch_scc1 .LBB0_234
	v_lshl_add_u64 v[146:147], v[204:205], 1, v[164:165]
	s_mov_b32 s98, 0x8000
	s_mov_b32 s99, 0
	v_mov_b32_e32 v252, v146
	v_mov_b32_e32 v253, v147
	global_load_dwordx2 v[228:229], v[252:253], off
	global_load_dwordx2 v[230:231], v[252:253], off offset:32
	global_load_dwordx2 v[232:233], v[252:253], off offset:256
	global_load_dwordx2 v[234:235], v[252:253], off offset:288
	v_lshl_add_u64 v[252:253], v[252:253], 0, s[98:99]
	global_load_dwordx2 v[236:237], v[252:253], off
	global_load_dwordx2 v[238:239], v[252:253], off offset:32
	global_load_dwordx2 v[240:241], v[252:253], off offset:256
	global_load_dwordx2 v[242:243], v[252:253], off offset:288
	v_lshl_add_u64 v[252:253], v[252:253], 0, s[98:99]
	global_load_dwordx2 v[244:245], v[252:253], off
	global_load_dwordx2 v[246:247], v[252:253], off offset:32
	s_waitcnt vmcnt(8)
	v_mov_b32_e32 v148, v228
	v_mov_b32_e32 v149, v229
	v_mov_b32_e32 v162, v230
	v_mov_b32_e32 v163, v231
	global_load_dwordx2 v[228:229], v[252:253], off offset:256
	global_load_dwordx2 v[230:231], v[252:253], off offset:288
	s_mov_b64 s[0:1], 0
	v_lshlrev_b32_e32 v150, 16, v148
	v_and_b32_e32 v151, 0xffff0000, v148
	v_lshlrev_b32_e32 v152, 16, v149
	v_and_b32_e32 v153, 0xffff0000, v149
	v_lshlrev_b32_e32 v146, 16, v162
	v_and_b32_e32 v147, 0xffff0000, v162
	v_lshlrev_b32_e32 v148, 16, v163
	v_and_b32_e32 v149, 0xffff0000, v163
	s_branch .LBB0_235

.LBB0_235:
	v_add_u32_e32 v154, 0xffffe000, v160
	v_lshlrev_b64 v[162:163], 12, v[154:155]
	s_andn2_b64 vcc, exec, s[0:1]
	v_lshl_add_u64 v[166:167], s[22:23], 0, v[162:163]
	v_lshl_add_u64 v[168:169], v[170:171], 2, s[20:21]
	s_cbranch_vccnz .LBB0_237
	v_cndmask_b32_e64 v147, v167, v169, s[2:3]
	v_cndmask_b32_e64 v146, v166, v168, s[2:3]
	v_lshl_add_u64 v[146:147], v[204:205], 2, v[146:147]
	global_load_dwordx4 v[150:153], v[146:147], off
	s_nop 0
	global_load_dwordx4 v[146:149], v[146:147], off offset:64
	s_waitcnt vmcnt(0)
.LBB0_237:
	v_and_b32_e32 v154, 16, v227
	s_add_u32 s24, s4, 0x4000000
	s_addc_u32 s25, s5, 0
	v_pk_fma_f32 v[150:151], v[142:143], v[110:111], v[150:151]
	v_add_u32_e32 v142, 12, v204
	v_cmp_eq_u32_e64 s[4:5], 0, v154
	v_pk_fma_f32 v[162:163], v[138:139], v[106:107], v[146:147]
	v_pk_fma_f32 v[152:153], v[144:145], v[112:113], v[152:153]
	v_cndmask_b32_e64 v146, v142, v204, s[4:5]
	v_pk_fma_f32 v[148:149], v[140:141], v[108:109], v[148:149]
	v_cvt_pk_bf16_f32 v138, v150, v151
	v_cvt_pk_bf16_f32 v139, v152, v153
	v_cvt_pk_bf16_f32 v140, v162, v163
	v_lshl_add_u64 v[170:171], v[170:171], 1, s[24:25]
	v_cvt_pk_bf16_f32 v141, v148, v149
	v_ashrrev_i32_e32 v147, 31, v146
	v_cndmask_b32_e64 v144, 0, 1, s[26:27]
	v_permlane16_swap_b32_e32 v138, v140
	v_permlane16_swap_b32_e32 v139, v141
	v_lshl_add_u64 v[142:143], v[146:147], 1, v[170:171]
	v_cmp_ne_u32_e64 s[0:1], 1, v144
	s_andn2_b64 vcc, exec, s[26:27]
	global_store_dwordx4 v[142:143], v[138:141], off
	s_cbranch_vccnz .LBB0_242
	s_nop 0
	v_lshl_add_u64 v[138:139], v[204:205], 1, v[164:165]
	s_waitcnt vmcnt(9)
	v_mov_b32_e32 v140, v232
	v_mov_b32_e32 v141, v233
	v_mov_b32_e32 v164, v234
	v_mov_b32_e32 v165, v235
	v_lshl_add_u64 v[252:253], v[252:253], 0, s[98:99]
	global_load_dwordx2 v[232:233], v[252:253], off
	global_load_dwordx2 v[234:235], v[252:253], off offset:32
	v_lshlrev_b32_e32 v142, 16, v140
	v_and_b32_e32 v143, 0xffff0000, v140
	v_lshlrev_b32_e32 v144, 16, v141
	v_and_b32_e32 v145, 0xffff0000, v141
	v_lshlrev_b32_e32 v138, 16, v164
	v_and_b32_e32 v139, 0xffff0000, v164
	v_lshlrev_b32_e32 v140, 16, v165
	v_and_b32_e32 v141, 0xffff0000, v165
	s_cbranch_execnz .LBB0_240
.LBB0_239:
	v_cndmask_b32_e64 v139, v167, v169, s[2:3]
	v_cndmask_b32_e64 v138, v166, v168, s[2:3]
	v_lshl_add_u64 v[138:139], v[204:205], 2, v[138:139]
	global_load_dwordx4 v[142:145], v[138:139], off offset:512
	s_nop 0
	global_load_dwordx4 v[138:141], v[138:139], off offset:576
	s_waitcnt vmcnt(0)
.LBB0_240:
	v_or_b32_e32 v206, 0x80, v204
	v_pk_fma_f32 v[142:143], v[134:135], v[94:95], v[142:143]
	v_pk_fma_f32 v[164:165], v[130:131], v[90:91], v[138:139]
	v_add_u32_e32 v134, 0x8c, v204
	v_or_b32_e32 v138, 16, v160
	v_cndmask_b32_e64 v166, v134, v206, s[4:5]
	v_ashrrev_i32_e32 v139, 31, v138
	v_pk_fma_f32 v[144:145], v[136:137], v[96:97], v[144:145]
	v_pk_fma_f32 v[140:141], v[132:133], v[92:93], v[140:141]
	v_cvt_pk_bf16_f32 v130, v142, v143
	v_cvt_pk_bf16_f32 v131, v144, v145
	v_cvt_pk_bf16_f32 v132, v164, v165
	v_ashrrev_i32_e32 v167, 31, v166
	v_cvt_pk_bf16_f32 v133, v140, v141
	v_lshlrev_b64 v[174:175], 10, v[138:139]
	s_movk_i32 s2, 0x2000
	v_permlane16_swap_b32_e32 v130, v132
	v_permlane16_swap_b32_e32 v131, v133
	v_lshl_add_u64 v[134:135], v[166:167], 1, v[170:171]
	v_cmp_gt_i32_e64 s[2:3], s2, v138
	s_and_b64 vcc, exec, s[0:1]
	v_lshl_add_u64 v[168:169], v[174:175], 1, s[16:17]
	global_store_dwordx4 v[134:135], v[130:133], off
	s_cbranch_vccnz .LBB0_243
	s_nop 0
	v_lshl_add_u64 v[130:131], v[204:205], 1, v[168:169]
	s_waitcnt vmcnt(10)
	v_mov_b32_e32 v132, v236
	v_mov_b32_e32 v133, v237
	v_mov_b32_e32 v170, v238
	v_mov_b32_e32 v171, v239
	global_load_dwordx2 v[236:237], v[252:253], off offset:256
	global_load_dwordx2 v[238:239], v[252:253], off offset:288
	s_mov_b64 s[4:5], 0
	v_lshlrev_b32_e32 v134, 16, v132
	v_and_b32_e32 v135, 0xffff0000, v132
	v_lshlrev_b32_e32 v136, 16, v133
	v_and_b32_e32 v137, 0xffff0000, v133
	v_lshlrev_b32_e32 v130, 16, v170
	v_and_b32_e32 v131, 0xffff0000, v170
	v_lshlrev_b32_e32 v132, 16, v171
	v_and_b32_e32 v133, 0xffff0000, v171
	s_branch .LBB0_244

.LBB0_244:
	v_add_u32_e32 v154, 0xffffe010, v160
	v_lshlrev_b64 v[170:171], 12, v[154:155]
	s_andn2_b64 vcc, exec, s[4:5]
	v_lshl_add_u64 v[170:171], s[22:23], 0, v[170:171]
	v_lshl_add_u64 v[172:173], v[174:175], 2, s[20:21]
	s_cbranch_vccnz .LBB0_246
	v_cndmask_b32_e64 v131, v171, v173, s[2:3]
	v_cndmask_b32_e64 v130, v170, v172, s[2:3]
	v_lshl_add_u64 v[130:131], v[204:205], 2, v[130:131]
	global_load_dwordx4 v[134:137], v[130:131], off
	s_nop 0
	global_load_dwordx4 v[130:133], v[130:131], off offset:64
	s_waitcnt vmcnt(0)
.LBB0_246:
	v_pk_fma_f32 v[136:137], v[128:129], v[112:113], v[136:137]
	v_pk_fma_f32 v[134:135], v[126:127], v[110:111], v[134:135]
	v_pk_fma_f32 v[132:133], v[124:125], v[108:109], v[132:133]
	v_pk_fma_f32 v[130:131], v[122:123], v[106:107], v[130:131]
	v_cvt_pk_bf16_f32 v122, v134, v135
	v_cvt_pk_bf16_f32 v123, v136, v137
	v_cvt_pk_bf16_f32 v125, v132, v133
	v_lshl_add_u64 v[174:175], v[174:175], 1, s[24:25]
	v_cvt_pk_bf16_f32 v124, v130, v131
	v_permlane16_swap_b32_e32 v123, v125
	v_permlane16_swap_b32_e32 v122, v124
	v_lshl_add_u64 v[126:127], v[146:147], 1, v[174:175]
	s_and_b64 vcc, exec, s[0:1]
	global_store_dwordx4 v[126:127], v[122:125], off
	s_cbranch_vccnz .LBB0_251
	s_nop 0
	v_lshl_add_u64 v[122:123], v[204:205], 1, v[168:169]
	s_waitcnt vmcnt(11)
	v_mov_b32_e32 v124, v240
	v_mov_b32_e32 v125, v241
	v_mov_b32_e32 v168, v242
	v_mov_b32_e32 v169, v243
	s_mov_b32 s98, 0x28000
	v_lshl_add_u64 v[252:253], v[252:253], 0, s[98:99]
	s_mov_b32 s98, 0x8000
	global_load_dwordx2 v[240:241], v[252:253], off
	global_load_dwordx2 v[242:243], v[252:253], off offset:32
	v_lshlrev_b32_e32 v126, 16, v124
	v_and_b32_e32 v127, 0xffff0000, v124
	v_lshlrev_b32_e32 v128, 16, v125
	v_and_b32_e32 v129, 0xffff0000, v125
	v_lshlrev_b32_e32 v122, 16, v168
	v_and_b32_e32 v123, 0xffff0000, v168
	v_lshlrev_b32_e32 v124, 16, v169
	v_and_b32_e32 v125, 0xffff0000, v169
	s_cbranch_execnz .LBB0_249
.LBB0_248:
	v_cndmask_b32_e64 v123, v171, v173, s[2:3]
	v_cndmask_b32_e64 v122, v170, v172, s[2:3]
	v_lshl_add_u64 v[122:123], v[204:205], 2, v[122:123]
	global_load_dwordx4 v[126:129], v[122:123], off offset:512
	s_nop 0
	global_load_dwordx4 v[122:125], v[122:123], off offset:576
	s_waitcnt vmcnt(0)
.LBB0_249:
	v_pk_fma_f32 v[170:171], v[114:115], v[90:91], v[122:123]
	v_or_b32_e32 v122, 32, v160
	v_ashrrev_i32_e32 v123, 31, v122
	v_pk_fma_f32 v[128:129], v[120:121], v[96:97], v[128:129]
	v_pk_fma_f32 v[126:127], v[118:119], v[94:95], v[126:127]
	v_pk_fma_f32 v[168:169], v[116:117], v[92:93], v[124:125]
	v_cvt_pk_bf16_f32 v114, v126, v127
	v_cvt_pk_bf16_f32 v115, v128, v129
	v_cvt_pk_bf16_f32 v116, v170, v171
	v_lshlrev_b64 v[176:177], 10, v[122:123]
	v_cvt_pk_bf16_f32 v117, v168, v169
	s_movk_i32 s2, 0x2000
	v_permlane16_swap_b32_e32 v114, v116
	v_permlane16_swap_b32_e32 v115, v117
	v_lshl_add_u64 v[118:119], v[166:167], 1, v[174:175]
	v_cmp_gt_i32_e64 s[2:3], s2, v122
	s_and_b64 vcc, exec, s[0:1]
	v_lshl_add_u64 v[124:125], v[176:177], 1, s[16:17]
	global_store_dwordx4 v[118:119], v[114:117], off
	s_cbranch_vccnz .LBB0_252
	s_nop 0
	v_lshl_add_u64 v[114:115], v[204:205], 1, v[124:125]
	s_waitcnt vmcnt(12)
	v_mov_b32_e32 v116, v244
	v_mov_b32_e32 v117, v245
	v_mov_b32_e32 v172, v246
	v_mov_b32_e32 v173, v247
	global_load_dwordx2 v[244:245], v[252:253], off offset:256
	global_load_dwordx2 v[246:247], v[252:253], off offset:288
	s_mov_b64 s[4:5], 0
	v_lshlrev_b32_e32 v118, 16, v116
	v_and_b32_e32 v119, 0xffff0000, v116
	v_lshlrev_b32_e32 v120, 16, v117
	v_and_b32_e32 v121, 0xffff0000, v117
	v_lshlrev_b32_e32 v114, 16, v172
	v_and_b32_e32 v115, 0xffff0000, v172
	v_lshlrev_b32_e32 v116, 16, v173
	v_and_b32_e32 v117, 0xffff0000, v173
	s_branch .LBB0_253

.LBB0_253:
	v_add_u32_e32 v154, 0xffffe020, v160
	v_lshlrev_b64 v[172:173], 12, v[154:155]
	s_andn2_b64 vcc, exec, s[4:5]
	v_lshl_add_u64 v[172:173], s[22:23], 0, v[172:173]
	v_lshl_add_u64 v[174:175], v[176:177], 2, s[20:21]
	s_cbranch_vccnz .LBB0_255
	v_cndmask_b32_e64 v115, v173, v175, s[2:3]
	v_cndmask_b32_e64 v114, v172, v174, s[2:3]
	v_lshl_add_u64 v[114:115], v[204:205], 2, v[114:115]
	global_load_dwordx4 v[118:121], v[114:115], off
	s_nop 0
	global_load_dwordx4 v[114:117], v[114:115], off offset:64
	s_waitcnt vmcnt(0)
.LBB0_255:
	v_pk_fma_f32 v[120:121], v[104:105], v[112:113], v[120:121]
	v_pk_fma_f32 v[118:119], v[102:103], v[110:111], v[118:119]
	v_pk_fma_f32 v[116:117], v[100:101], v[108:109], v[116:117]
	v_pk_fma_f32 v[114:115], v[98:99], v[106:107], v[114:115]
	v_cvt_pk_bf16_f32 v98, v118, v119
	v_cvt_pk_bf16_f32 v99, v120, v121
	v_cvt_pk_bf16_f32 v101, v116, v117
	v_lshl_add_u64 v[176:177], v[176:177], 1, s[24:25]
	v_cvt_pk_bf16_f32 v100, v114, v115
	v_permlane16_swap_b32_e32 v99, v101
	v_permlane16_swap_b32_e32 v98, v100
	v_lshl_add_u64 v[102:103], v[146:147], 1, v[176:177]
	s_and_b64 vcc, exec, s[0:1]
	global_store_dwordx4 v[102:103], v[98:101], off
	s_cbranch_vccnz .LBB0_260
	s_nop 0
	v_lshl_add_u64 v[98:99], v[204:205], 1, v[124:125]
	s_waitcnt vmcnt(13)
	v_mov_b32_e32 v100, v228
	v_mov_b32_e32 v101, v229
	v_mov_b32_e32 v124, v230
	v_mov_b32_e32 v125, v231
	v_lshl_add_u64 v[252:253], v[252:253], 0, s[98:99]
	global_load_dwordx2 v[228:229], v[252:253], off
	global_load_dwordx2 v[230:231], v[252:253], off offset:32
	v_lshlrev_b32_e32 v102, 16, v100
	v_and_b32_e32 v103, 0xffff0000, v100
	v_lshlrev_b32_e32 v104, 16, v101
	v_and_b32_e32 v105, 0xffff0000, v101
	v_lshlrev_b32_e32 v98, 16, v124
	v_and_b32_e32 v99, 0xffff0000, v124
	v_lshlrev_b32_e32 v100, 16, v125
	v_and_b32_e32 v101, 0xffff0000, v125
	s_cbranch_execnz .LBB0_258
.LBB0_257:
	v_cndmask_b32_e64 v99, v173, v175, s[2:3]
	v_cndmask_b32_e64 v98, v172, v174, s[2:3]
	v_lshl_add_u64 v[98:99], v[204:205], 2, v[98:99]
	global_load_dwordx4 v[102:105], v[98:99], off offset:512
	s_nop 0
	global_load_dwordx4 v[98:101], v[98:99], off offset:576
	s_waitcnt vmcnt(0)
.LBB0_258:
	v_pk_fma_f32 v[124:125], v[82:83], v[90:91], v[98:99]
	v_or_b32_e32 v98, 48, v160
	v_ashrrev_i32_e32 v99, 31, v98
	v_pk_fma_f32 v[104:105], v[88:89], v[96:97], v[104:105]
	v_pk_fma_f32 v[102:103], v[86:87], v[94:95], v[102:103]
	v_pk_fma_f32 v[100:101], v[84:85], v[92:93], v[100:101]
	v_cvt_pk_bf16_f32 v82, v102, v103
	v_cvt_pk_bf16_f32 v83, v104, v105
	v_cvt_pk_bf16_f32 v84, v124, v125
	v_lshlrev_b64 v[178:179], 10, v[98:99]
	v_cvt_pk_bf16_f32 v85, v100, v101
	s_movk_i32 s2, 0x2000
	v_permlane16_swap_b32_e32 v82, v84
	v_permlane16_swap_b32_e32 v83, v85
	v_lshl_add_u64 v[86:87], v[166:167], 1, v[176:177]
	v_cmp_gt_i32_e64 s[2:3], s2, v98
	s_and_b64 vcc, exec, s[0:1]
	v_lshl_add_u64 v[172:173], v[178:179], 1, s[16:17]
	global_store_dwordx4 v[86:87], v[82:85], off
	s_cbranch_vccnz .LBB0_261
	s_nop 0
	v_lshl_add_u64 v[82:83], v[204:205], 1, v[172:173]
	s_waitcnt vmcnt(13)
	v_mov_b32_e32 v84, v232
	v_mov_b32_e32 v85, v233
	v_mov_b32_e32 v174, v234
	v_mov_b32_e32 v175, v235
	global_load_dwordx2 v[232:233], v[252:253], off offset:256
	global_load_dwordx2 v[234:235], v[252:253], off offset:288
	s_mov_b64 s[4:5], 0
	v_lshlrev_b32_e32 v86, 16, v84
	v_and_b32_e32 v87, 0xffff0000, v84
	v_lshlrev_b32_e32 v88, 16, v85
	v_and_b32_e32 v89, 0xffff0000, v85
	v_lshlrev_b32_e32 v82, 16, v174
	v_and_b32_e32 v83, 0xffff0000, v174
	v_lshlrev_b32_e32 v84, 16, v175
	v_and_b32_e32 v85, 0xffff0000, v175
	s_branch .LBB0_262

.LBB0_262:
	v_add_u32_e32 v154, 0xffffe030, v160
	v_lshlrev_b64 v[174:175], 12, v[154:155]
	s_andn2_b64 vcc, exec, s[4:5]
	v_lshl_add_u64 v[174:175], s[22:23], 0, v[174:175]
	v_lshl_add_u64 v[176:177], v[178:179], 2, s[20:21]
	s_cbranch_vccnz .LBB0_264
	v_cndmask_b32_e64 v83, v175, v177, s[2:3]
	v_cndmask_b32_e64 v82, v174, v176, s[2:3]
	v_lshl_add_u64 v[82:83], v[204:205], 2, v[82:83]
	global_load_dwordx4 v[86:89], v[82:83], off
	s_nop 0
	global_load_dwordx4 v[82:85], v[82:83], off offset:64
	s_waitcnt vmcnt(0)
.LBB0_264:
	v_pk_fma_f32 v[88:89], v[80:81], v[112:113], v[88:89]
	v_pk_fma_f32 v[86:87], v[78:79], v[110:111], v[86:87]
	v_pk_fma_f32 v[84:85], v[76:77], v[108:109], v[84:85]
	v_pk_fma_f32 v[82:83], v[74:75], v[106:107], v[82:83]
	v_cvt_pk_bf16_f32 v74, v86, v87
	v_cvt_pk_bf16_f32 v75, v88, v89
	v_cvt_pk_bf16_f32 v77, v84, v85
	v_lshl_add_u64 v[178:179], v[178:179], 1, s[24:25]
	v_cvt_pk_bf16_f32 v76, v82, v83
	v_permlane16_swap_b32_e32 v75, v77
	v_permlane16_swap_b32_e32 v74, v76
	v_lshl_add_u64 v[78:79], v[146:147], 1, v[178:179]
	s_and_b64 vcc, exec, s[0:1]
	global_store_dwordx4 v[78:79], v[74:77], off
	s_cbranch_vccnz .LBB0_269
	s_nop 0
	v_lshl_add_u64 v[74:75], v[204:205], 1, v[172:173]
	s_waitcnt vmcnt(13)
	v_mov_b32_e32 v76, v236
	v_mov_b32_e32 v77, v237
	v_mov_b32_e32 v172, v238
	v_mov_b32_e32 v173, v239
	v_lshl_add_u64 v[252:253], v[252:253], 0, s[98:99]
	global_load_dwordx2 v[236:237], v[252:253], off
	global_load_dwordx2 v[238:239], v[252:253], off offset:32
	v_lshlrev_b32_e32 v78, 16, v76
	v_and_b32_e32 v79, 0xffff0000, v76
	v_lshlrev_b32_e32 v80, 16, v77
	v_and_b32_e32 v81, 0xffff0000, v77
	v_lshlrev_b32_e32 v74, 16, v172
	v_and_b32_e32 v75, 0xffff0000, v172
	v_lshlrev_b32_e32 v76, 16, v173
	v_and_b32_e32 v77, 0xffff0000, v173
	s_cbranch_execnz .LBB0_267
.LBB0_266:
	v_cndmask_b32_e64 v75, v175, v177, s[2:3]
	v_cndmask_b32_e64 v74, v174, v176, s[2:3]
	v_lshl_add_u64 v[74:75], v[204:205], 2, v[74:75]
	global_load_dwordx4 v[78:81], v[74:75], off offset:512
	s_nop 0
	global_load_dwordx4 v[74:77], v[74:75], off offset:576
	s_waitcnt vmcnt(0)
.LBB0_267:
	v_pk_fma_f32 v[186:187], v[66:67], v[90:91], v[74:75]
	v_add_u32_e32 v74, 0x80, v160
	v_ashrrev_i32_e32 v75, 31, v74
	v_pk_fma_f32 v[176:177], v[72:73], v[96:97], v[80:81]
	v_pk_fma_f32 v[180:181], v[70:71], v[94:95], v[78:79]
	v_pk_fma_f32 v[184:185], v[68:69], v[92:93], v[76:77]
	v_cvt_pk_bf16_f32 v66, v180, v181
	v_cvt_pk_bf16_f32 v67, v176, v177
	v_cvt_pk_bf16_f32 v68, v186, v187
	v_lshlrev_b64 v[172:173], 10, v[74:75]
	v_cvt_pk_bf16_f32 v69, v184, v185
	s_movk_i32 s2, 0x1f80
	v_permlane16_swap_b32_e32 v66, v68
	v_permlane16_swap_b32_e32 v67, v69
	v_lshl_add_u64 v[70:71], v[166:167], 1, v[178:179]
	v_cmp_gt_i32_e64 s[2:3], s2, v160
	s_and_b64 vcc, exec, s[0:1]
	v_lshl_add_u64 v[76:77], v[172:173], 1, s[16:17]
	global_store_dwordx4 v[70:71], v[66:69], off
	s_cbranch_vccnz .LBB0_270
	s_nop 0
	v_lshl_add_u64 v[66:67], v[204:205], 1, v[76:77]
	s_waitcnt vmcnt(13)
	v_mov_b32_e32 v68, v240
	v_mov_b32_e32 v69, v241
	v_mov_b32_e32 v78, v242
	v_mov_b32_e32 v79, v243
	global_load_dwordx2 v[240:241], v[252:253], off offset:256
	global_load_dwordx2 v[242:243], v[252:253], off offset:288
	s_mov_b64 s[4:5], 0
	v_lshlrev_b32_e32 v70, 16, v68
	v_and_b32_e32 v71, 0xffff0000, v68
	v_lshlrev_b32_e32 v72, 16, v69
	v_and_b32_e32 v73, 0xffff0000, v69
	v_lshlrev_b32_e32 v66, 16, v78
	v_and_b32_e32 v67, 0xffff0000, v78
	v_lshlrev_b32_e32 v68, 16, v79
	v_and_b32_e32 v69, 0xffff0000, v79
	s_branch .LBB0_271

.LBB0_271:
	v_add_u32_e32 v154, 0xffffe080, v160
	v_lshlrev_b64 v[78:79], 12, v[154:155]
	s_andn2_b64 vcc, exec, s[4:5]
	v_lshl_add_u64 v[78:79], s[22:23], 0, v[78:79]
	v_lshl_add_u64 v[80:81], v[172:173], 2, s[20:21]
	s_cbranch_vccnz .LBB0_273
	v_cndmask_b32_e64 v67, v79, v81, s[2:3]
	v_cndmask_b32_e64 v66, v78, v80, s[2:3]
	v_lshl_add_u64 v[66:67], v[204:205], 2, v[66:67]
	global_load_dwordx4 v[70:73], v[66:67], off
	s_nop 0
	global_load_dwordx4 v[66:69], v[66:67], off offset:64
	s_waitcnt vmcnt(0)
.LBB0_273:
	v_pk_fma_f32 v[72:73], v[64:65], v[112:113], v[72:73]
	v_pk_fma_f32 v[70:71], v[62:63], v[110:111], v[70:71]
	v_pk_fma_f32 v[68:69], v[60:61], v[108:109], v[68:69]
	v_pk_fma_f32 v[66:67], v[58:59], v[106:107], v[66:67]
	v_cvt_pk_bf16_f32 v58, v70, v71
	v_cvt_pk_bf16_f32 v59, v72, v73
	v_cvt_pk_bf16_f32 v61, v68, v69
	v_lshl_add_u64 v[188:189], v[172:173], 1, s[24:25]
	v_cvt_pk_bf16_f32 v60, v66, v67
	v_permlane16_swap_b32_e32 v59, v61
	v_permlane16_swap_b32_e32 v58, v60
	v_lshl_add_u64 v[62:63], v[146:147], 1, v[188:189]
	s_and_b64 vcc, exec, s[0:1]
	global_store_dwordx4 v[62:63], v[58:61], off
	s_cbranch_vccnz .LBB0_278
	s_nop 0
	v_lshl_add_u64 v[58:59], v[204:205], 1, v[76:77]
	s_waitcnt vmcnt(13)
	v_mov_b32_e32 v60, v244
	v_mov_b32_e32 v61, v245
	v_mov_b32_e32 v76, v246
	v_mov_b32_e32 v77, v247
	v_lshl_add_u64 v[252:253], v[252:253], 0, s[98:99]
	global_load_dwordx2 v[244:245], v[252:253], off
	global_load_dwordx2 v[246:247], v[252:253], off offset:32
	v_lshlrev_b32_e32 v62, 16, v60
	v_and_b32_e32 v63, 0xffff0000, v60
	v_lshlrev_b32_e32 v64, 16, v61
	v_and_b32_e32 v65, 0xffff0000, v61
	v_lshlrev_b32_e32 v58, 16, v76
	v_and_b32_e32 v59, 0xffff0000, v76
	v_lshlrev_b32_e32 v60, 16, v77
	v_and_b32_e32 v61, 0xffff0000, v77
	s_cbranch_execnz .LBB0_276
.LBB0_275:
	v_cndmask_b32_e64 v59, v79, v81, s[2:3]
	v_cndmask_b32_e64 v58, v78, v80, s[2:3]
	v_lshl_add_u64 v[58:59], v[204:205], 2, v[58:59]
	global_load_dwordx4 v[62:65], v[58:59], off offset:512
	s_nop 0
	global_load_dwordx4 v[58:61], v[58:59], off offset:576
	s_waitcnt vmcnt(0)
.LBB0_276:
	v_pk_fma_f32 v[182:183], v[50:51], v[90:91], v[58:59]
	v_add_u32_e32 v58, 0x90, v160
	v_ashrrev_i32_e32 v59, 31, v58
	v_pk_fma_f32 v[172:173], v[56:57], v[96:97], v[64:65]
	v_pk_fma_f32 v[174:175], v[54:55], v[94:95], v[62:63]
	v_pk_fma_f32 v[178:179], v[52:53], v[92:93], v[60:61]
	v_cvt_pk_bf16_f32 v50, v174, v175
	v_cvt_pk_bf16_f32 v51, v172, v173
	v_cvt_pk_bf16_f32 v52, v182, v183
	v_lshlrev_b64 v[190:191], 10, v[58:59]
	v_cvt_pk_bf16_f32 v53, v178, v179
	s_movk_i32 s2, 0x1f70
	v_permlane16_swap_b32_e32 v50, v52
	v_permlane16_swap_b32_e32 v51, v53
	v_lshl_add_u64 v[54:55], v[166:167], 1, v[188:189]
	v_cmp_gt_i32_e64 s[2:3], s2, v160
	s_and_b64 vcc, exec, s[0:1]
	v_lshl_add_u64 v[62:63], v[190:191], 1, s[16:17]
	global_store_dwordx4 v[54:55], v[50:53], off
	s_cbranch_vccnz .LBB0_279
	s_nop 0
	v_lshl_add_u64 v[50:51], v[204:205], 1, v[62:63]
	s_waitcnt vmcnt(13)
	v_mov_b32_e32 v52, v228
	v_mov_b32_e32 v53, v229
	v_mov_b32_e32 v60, v230
	v_mov_b32_e32 v61, v231
	global_load_dwordx2 v[228:229], v[252:253], off offset:256
	global_load_dwordx2 v[230:231], v[252:253], off offset:288
	s_mov_b64 s[4:5], 0
	v_lshlrev_b32_e32 v54, 16, v52
	v_and_b32_e32 v55, 0xffff0000, v52
	v_lshlrev_b32_e32 v56, 16, v53
	v_and_b32_e32 v57, 0xffff0000, v53
	v_lshlrev_b32_e32 v50, 16, v60
	v_and_b32_e32 v51, 0xffff0000, v60
	v_lshlrev_b32_e32 v52, 16, v61
	v_and_b32_e32 v53, 0xffff0000, v61
	s_branch .LBB0_280

.LBB0_280:
	v_add_u32_e32 v154, 0xffffe090, v160
	v_lshlrev_b64 v[60:61], 12, v[154:155]
	s_andn2_b64 vcc, exec, s[4:5]
	v_lshl_add_u64 v[76:77], s[22:23], 0, v[60:61]
	v_lshl_add_u64 v[188:189], v[190:191], 2, s[20:21]
	s_cbranch_vccnz .LBB0_282
	v_cndmask_b32_e64 v51, v77, v189, s[2:3]
	v_cndmask_b32_e64 v50, v76, v188, s[2:3]
	v_lshl_add_u64 v[50:51], v[204:205], 2, v[50:51]
	global_load_dwordx4 v[54:57], v[50:51], off
	s_nop 0
	global_load_dwordx4 v[50:53], v[50:51], off offset:64
	s_waitcnt vmcnt(0)
.LBB0_282:
	v_pk_fma_f32 v[60:61], v[48:49], v[112:113], v[56:57]
	v_pk_fma_f32 v[64:65], v[46:47], v[110:111], v[54:55]
	v_pk_fma_f32 v[78:79], v[44:45], v[108:109], v[52:53]
	v_pk_fma_f32 v[80:81], v[42:43], v[106:107], v[50:51]
	v_cvt_pk_bf16_f32 v42, v64, v65
	v_cvt_pk_bf16_f32 v43, v60, v61
	v_cvt_pk_bf16_f32 v45, v78, v79
	v_lshl_add_u64 v[50:51], v[190:191], 1, s[24:25]
	v_cvt_pk_bf16_f32 v44, v80, v81
	v_permlane16_swap_b32_e32 v43, v45
	v_permlane16_swap_b32_e32 v42, v44
	v_lshl_add_u64 v[46:47], v[146:147], 1, v[50:51]
	s_and_b64 vcc, exec, s[0:1]
	global_store_dwordx4 v[46:47], v[42:45], off
	s_cbranch_vccnz .LBB0_287
	s_nop 0
	v_lshl_add_u64 v[42:43], v[204:205], 1, v[62:63]
	s_waitcnt vmcnt(13)
	v_mov_b32_e32 v44, v232
	v_mov_b32_e32 v45, v233
	v_mov_b32_e32 v52, v234
	v_mov_b32_e32 v53, v235
	v_lshlrev_b32_e32 v46, 16, v44
	v_and_b32_e32 v47, 0xffff0000, v44
	v_lshlrev_b32_e32 v48, 16, v45
	v_and_b32_e32 v49, 0xffff0000, v45
	v_lshlrev_b32_e32 v42, 16, v52
	v_and_b32_e32 v43, 0xffff0000, v52
	v_lshlrev_b32_e32 v44, 16, v53
	v_and_b32_e32 v45, 0xffff0000, v53
	s_cbranch_execnz .LBB0_285
.LBB0_284:
	v_cndmask_b32_e64 v43, v77, v189, s[2:3]
	v_cndmask_b32_e64 v42, v76, v188, s[2:3]
	v_lshl_add_u64 v[42:43], v[204:205], 2, v[42:43]
	global_load_dwordx4 v[46:49], v[42:43], off offset:512
	s_nop 0
	global_load_dwordx4 v[42:45], v[42:43], off offset:576
	s_waitcnt vmcnt(0)
.LBB0_285:
	v_pk_fma_f32 v[196:197], v[38:39], v[94:95], v[46:47]
	v_lshl_add_u64 v[38:39], v[166:167], 1, v[50:51]
	v_add_u32_e32 v50, 0xa0, v160
	v_ashrrev_i32_e32 v51, 31, v50
	v_pk_fma_f32 v[192:193], v[40:41], v[96:97], v[48:49]
	v_pk_fma_f32 v[200:201], v[36:37], v[92:93], v[44:45]
	v_pk_fma_f32 v[202:203], v[34:35], v[90:91], v[42:43]
	v_cvt_pk_bf16_f32 v34, v196, v197
	v_cvt_pk_bf16_f32 v35, v192, v193
	v_cvt_pk_bf16_f32 v37, v200, v201
	v_lshlrev_b64 v[48:49], 10, v[50:51]
	v_cvt_pk_bf16_f32 v36, v202, v203
	s_movk_i32 s2, 0x1f60
	v_permlane16_swap_b32_e32 v34, v36
	v_permlane16_swap_b32_e32 v35, v37
	v_cmp_gt_i32_e64 s[2:3], s2, v160
	s_and_b64 vcc, exec, s[0:1]
	v_lshl_add_u64 v[42:43], v[48:49], 1, s[16:17]
	global_store_dwordx4 v[38:39], v[34:37], off
	s_cbranch_vccnz .LBB0_288
	s_nop 0
	v_lshl_add_u64 v[34:35], v[204:205], 1, v[42:43]
	s_waitcnt vmcnt(11)
	v_mov_b32_e32 v36, v236
	v_mov_b32_e32 v37, v237
	v_mov_b32_e32 v44, v238
	v_mov_b32_e32 v45, v239
	s_mov_b64 s[4:5], 0
	v_lshlrev_b32_e32 v38, 16, v36
	v_and_b32_e32 v39, 0xffff0000, v36
	v_lshlrev_b32_e32 v40, 16, v37
	v_and_b32_e32 v41, 0xffff0000, v37
	v_lshlrev_b32_e32 v34, 16, v44
	v_and_b32_e32 v35, 0xffff0000, v44
	v_lshlrev_b32_e32 v36, 16, v45
	v_and_b32_e32 v37, 0xffff0000, v45
	s_branch .LBB0_289

.LBB0_289:
	v_add_u32_e32 v154, 0xffffe0a0, v160
	v_lshlrev_b64 v[44:45], 12, v[154:155]
	s_andn2_b64 vcc, exec, s[4:5]
	v_lshl_add_u64 v[44:45], s[22:23], 0, v[44:45]
	v_lshl_add_u64 v[46:47], v[48:49], 2, s[20:21]
	s_cbranch_vccnz .LBB0_291
	v_cndmask_b32_e64 v35, v45, v47, s[2:3]
	v_cndmask_b32_e64 v34, v44, v46, s[2:3]
	v_lshl_add_u64 v[34:35], v[204:205], 2, v[34:35]
	global_load_dwordx4 v[38:41], v[34:35], off
	s_nop 0
	global_load_dwordx4 v[34:37], v[34:35], off offset:64
	s_waitcnt vmcnt(0)
.LBB0_291:
	v_pk_fma_f32 v[54:55], v[32:33], v[112:113], v[40:41]
	v_pk_fma_f32 v[56:57], v[30:31], v[110:111], v[38:39]
	v_pk_fma_f32 v[62:63], v[28:29], v[108:109], v[36:37]
	v_pk_fma_f32 v[76:77], v[26:27], v[106:107], v[34:35]
	v_cvt_pk_bf16_f32 v26, v56, v57
	v_cvt_pk_bf16_f32 v27, v54, v55
	v_cvt_pk_bf16_f32 v29, v62, v63
	v_lshl_add_u64 v[34:35], v[48:49], 1, s[24:25]
	v_cvt_pk_bf16_f32 v28, v76, v77
	v_permlane16_swap_b32_e32 v27, v29
	v_permlane16_swap_b32_e32 v26, v28
	v_lshl_add_u64 v[30:31], v[146:147], 1, v[34:35]
	s_and_b64 vcc, exec, s[0:1]
	global_store_dwordx4 v[30:31], v[26:29], off
	s_cbranch_vccnz .LBB0_296
	s_nop 0
	v_lshl_add_u64 v[26:27], v[204:205], 1, v[42:43]
	s_waitcnt vmcnt(9)
	v_mov_b32_e32 v28, v240
	v_mov_b32_e32 v29, v241
	v_mov_b32_e32 v36, v242
	v_mov_b32_e32 v37, v243
	v_lshlrev_b32_e32 v30, 16, v28
	v_and_b32_e32 v31, 0xffff0000, v28
	v_lshlrev_b32_e32 v32, 16, v29
	v_and_b32_e32 v33, 0xffff0000, v29
	v_lshlrev_b32_e32 v26, 16, v36
	v_and_b32_e32 v27, 0xffff0000, v36
	v_lshlrev_b32_e32 v28, 16, v37
	v_and_b32_e32 v29, 0xffff0000, v37
	s_cbranch_execnz .LBB0_294
.LBB0_293:
	v_cndmask_b32_e64 v27, v45, v47, s[2:3]
	v_cndmask_b32_e64 v26, v44, v46, s[2:3]
	v_lshl_add_u64 v[26:27], v[204:205], 2, v[26:27]
	global_load_dwordx4 v[30:33], v[26:27], off offset:512
	s_nop 0
	global_load_dwordx4 v[26:29], v[26:27], off offset:576
	s_waitcnt vmcnt(0)
.LBB0_294:
	v_add_u32_e32 v52, 0xb0, v160
	v_ashrrev_i32_e32 v53, 31, v52
	v_pk_fma_f32 v[188:189], v[24:25], v[96:97], v[32:33]
	v_pk_fma_f32 v[190:191], v[22:23], v[94:95], v[30:31]
	v_pk_fma_f32 v[194:195], v[20:21], v[92:93], v[28:29]
	v_pk_fma_f32 v[198:199], v[18:19], v[90:91], v[26:27]
	v_cvt_pk_bf16_f32 v18, v190, v191
	v_cvt_pk_bf16_f32 v19, v188, v189
	v_cvt_pk_bf16_f32 v21, v194, v195
	v_lshlrev_b64 v[32:33], 10, v[52:53]
	v_cvt_pk_bf16_f32 v20, v198, v199
	s_movk_i32 s2, 0x1f50
	v_permlane16_swap_b32_e32 v18, v20
	v_permlane16_swap_b32_e32 v19, v21
	v_lshl_add_u64 v[22:23], v[166:167], 1, v[34:35]
	v_cmp_gt_i32_e64 s[2:3], s2, v160
	s_and_b64 vcc, exec, s[0:1]
	v_lshl_add_u64 v[26:27], v[32:33], 1, s[16:17]
	global_store_dwordx4 v[22:23], v[18:21], off
	s_cbranch_vccnz .LBB0_297
	s_nop 0
	v_lshl_add_u64 v[18:19], v[204:205], 1, v[26:27]
	s_waitcnt vmcnt(7)
	v_mov_b32_e32 v20, v244
	v_mov_b32_e32 v21, v245
	v_mov_b32_e32 v28, v246
	v_mov_b32_e32 v29, v247
	s_mov_b64 s[4:5], 0
	v_lshlrev_b32_e32 v22, 16, v20
	v_and_b32_e32 v23, 0xffff0000, v20
	v_lshlrev_b32_e32 v24, 16, v21
	v_and_b32_e32 v25, 0xffff0000, v21
	v_lshlrev_b32_e32 v18, 16, v28
	v_and_b32_e32 v19, 0xffff0000, v28
	v_lshlrev_b32_e32 v20, 16, v29
	v_and_b32_e32 v21, 0xffff0000, v29
	s_branch .LBB0_298

.LBB0_298:
	v_add_u32_e32 v154, 0xffffe0b0, v160
	v_lshlrev_b64 v[28:29], 12, v[154:155]
	s_andn2_b64 vcc, exec, s[4:5]
	v_lshl_add_u64 v[28:29], s[22:23], 0, v[28:29]
	v_lshl_add_u64 v[30:31], v[32:33], 2, s[20:21]
	s_cbranch_vccnz .LBB0_300
	v_cndmask_b32_e64 v19, v29, v31, s[2:3]
	v_cndmask_b32_e64 v18, v28, v30, s[2:3]
	v_lshl_add_u64 v[18:19], v[204:205], 2, v[18:19]
	global_load_dwordx4 v[22:25], v[18:19], off
	s_nop 0
	global_load_dwordx4 v[18:21], v[18:19], off offset:64
	s_waitcnt vmcnt(0)
.LBB0_300:
	v_pk_fma_f32 v[112:113], v[16:17], v[112:113], v[24:25]
	v_pk_fma_f32 v[110:111], v[14:15], v[110:111], v[22:23]
	v_pk_fma_f32 v[108:109], v[12:13], v[108:109], v[20:21]
	v_pk_fma_f32 v[106:107], v[10:11], v[106:107], v[18:19]
	v_cvt_pk_bf16_f32 v10, v110, v111
	v_cvt_pk_bf16_f32 v11, v112, v113
	v_cvt_pk_bf16_f32 v13, v108, v109
	v_lshl_add_u64 v[18:19], v[32:33], 1, s[24:25]
	v_cvt_pk_bf16_f32 v12, v106, v107
	v_permlane16_swap_b32_e32 v11, v13
	v_permlane16_swap_b32_e32 v10, v12
	v_lshl_add_u64 v[14:15], v[146:147], 1, v[18:19]
	s_and_b64 vcc, exec, s[0:1]
	global_store_dwordx4 v[14:15], v[10:13], off
	s_cbranch_vccnz .LBB0_337
	s_nop 0
	v_lshl_add_u64 v[10:11], v[204:205], 1, v[26:27]
	s_waitcnt vmcnt(5)
	v_mov_b32_e32 v12, v228
	v_mov_b32_e32 v13, v229
	v_mov_b32_e32 v20, v230
	v_mov_b32_e32 v21, v231
	v_lshlrev_b32_e32 v14, 16, v12
	v_and_b32_e32 v15, 0xffff0000, v12
	v_lshlrev_b32_e32 v16, 16, v13
	v_and_b32_e32 v17, 0xffff0000, v13
	v_lshlrev_b32_e32 v10, 16, v20
	v_and_b32_e32 v11, 0xffff0000, v20
	v_lshlrev_b32_e32 v12, 16, v21
	v_and_b32_e32 v13, 0xffff0000, v21
	s_cbranch_execnz .LBB0_303
.LBB0_302:
	v_cndmask_b32_e64 v11, v29, v31, s[2:3]
	v_cndmask_b32_e64 v10, v28, v30, s[2:3]
	v_lshl_add_u64 v[10:11], v[204:205], 2, v[10:11]
	global_load_dwordx4 v[14:17], v[10:11], off offset:512
	s_nop 0
	global_load_dwordx4 v[10:13], v[10:11], off offset:576
	s_waitcnt vmcnt(0)
.LBB0_303:
	v_readlane_b32 s0, v254, 3
	v_readlane_b32 s2, v254, 5
	v_readlane_b32 s1, v254, 4
	v_readlane_b32 s3, v254, 6
	s_add_u32 s0, s2, 0
	s_addc_u32 s1, s3, s42
	s_add_u32 s0, s0, s41
	s_addc_u32 s1, s1, 0
	s_lshl_b32 s2, s92, 12
	s_add_u32 s0, s0, s2
	s_addc_u32 s1, s1, 0
	s_add_u32 s2, s18, 0x4000
	v_pk_fma_f32 v[96:97], v[8:9], v[96:97], v[16:17]
	v_pk_fma_f32 v[94:95], v[6:7], v[94:95], v[14:15]
	v_pk_fma_f32 v[92:93], v[4:5], v[92:93], v[12:13]
	v_pk_fma_f32 v[90:91], v[2:3], v[90:91], v[10:11]
	v_cvt_pk_bf16_f32 v2, v94, v95
	v_cvt_pk_bf16_f32 v3, v96, v97
	v_cvt_pk_bf16_f32 v5, v92, v93
	s_addc_u32 s3, s19, 0
	v_cvt_pk_bf16_f32 v4, v90, v91
	v_permlane16_swap_b32_e32 v3, v5
	v_permlane16_swap_b32_e32 v2, v4
	v_lshl_add_u64 v[6:7], v[166:167], 1, v[18:19]
	s_add_u32 s4, s18, 0x3000
	global_store_dwordx4 v[6:7], v[2:5], off
	s_addc_u32 s5, s19, 0
	v_ashrrev_i32_e32 v207, 31, v206
	v_lshlrev_b64 v[2:3], 2, v[204:205]
	v_lshl_add_u64 v[6:7], s[0:1], 0, v[2:3]
	v_lshl_add_u64 v[4:5], s[2:3], 0, v[2:3]
	v_lshl_add_u64 v[2:3], s[4:5], 0, v[2:3]
	global_load_dwordx4 v[18:21], v[4:5], off
	global_load_dwordx4 v[10:13], v[2:3], off
	v_or_b32_e32 v2, 16, v204
	v_ashrrev_i32_e32 v3, 31, v2
	v_lshlrev_b64 v[2:3], 2, v[2:3]
	v_lshl_add_u64 v[4:5], s[2:3], 0, v[2:3]
	v_lshl_add_u64 v[2:3], s[4:5], 0, v[2:3]
	global_load_dwordx4 v[22:25], v[6:7], off
	global_load_dwordx4 v[26:29], v[6:7], off offset:64
	global_load_dwordx4 v[30:33], v[4:5], off
	global_load_dwordx4 v[14:17], v[2:3], off
	v_lshlrev_b64 v[2:3], 2, v[206:207]
	v_or_b32_e32 v8, 0x90, v204
	v_lshl_add_u64 v[4:5], s[2:3], 0, v[2:3]
	v_lshl_add_u64 v[2:3], s[4:5], 0, v[2:3]
	v_ashrrev_i32_e32 v9, 31, v8
	global_load_dwordx4 v[34:37], v[4:5], off
	s_nop 0
	global_load_dwordx4 v[2:5], v[2:3], off
	s_nop 0
	global_load_dwordx4 v[38:41], v[6:7], off offset:512
	global_load_dwordx4 v[42:45], v[6:7], off offset:576
	v_lshlrev_b64 v[6:7], 2, v[8:9]
	v_lshl_add_u64 v[8:9], s[2:3], 0, v[6:7]
	v_lshl_add_u64 v[6:7], s[4:5], 0, v[6:7]
	global_load_dwordx4 v[46:49], v[8:9], off
	s_nop 0
	global_load_dwordx4 v[6:9], v[6:7], off
	v_mov_b32_e32 v204, v151
	v_mov_b32_e32 v205, v152
	v_mov_b32_e32 v206, v150
	v_mov_b32_e32 v207, v153
	v_pk_add_f32 v[204:205], v[204:205], v[206:207]
	v_mov_b32_e32 v206, v163
	v_mov_b32_e32 v207, v148
	v_mov_b32_e32 v228, v162
	v_mov_b32_e32 v229, v149
	v_pk_add_f32 v[206:207], v[206:207], v[228:229]
	v_add_f32_e32 v204, v204, v205
	v_pk_add_f32 v[206:207], v[206:207], v[206:207] op_sel_hi:[0,1]
	v_xor_b32_e32 v154, 16, v214
	v_add_f32_e32 v205, 0, v204
	v_add_f32_e32 v229, v142, v143
	v_add_f32_e32 v231, v144, v145
	v_mov_b32_e32 v206, v164
	v_mov_b32_e32 v204, v165
	v_mov_b32_e32 v228, v140
	v_mov_b32_e32 v230, v141
	v_cmp_lt_i32_e32 vcc, v154, v216
	v_pk_add_f32 v[204:205], v[206:207], v[204:205]
	v_pk_add_f32 v[206:207], v[228:229], v[230:231]
	v_cndmask_b32_e32 v154, v214, v154, vcc
	v_pk_add_f32 v[204:205], v[204:205], v[206:207]
	v_lshlrev_b32_e32 v154, 2, v154
	v_add_f32_e32 v205, v204, v205
	ds_bpermute_b32 v206, v154, v205
	v_cmp_lt_i32_e32 vcc, v215, v216
	v_mov_b32_e32 v229, v151
	v_mov_b32_e32 v230, v163
	v_cndmask_b32_e32 v204, v214, v215, vcc
	v_lshlrev_b32_e32 v204, 2, v204
	s_waitcnt lgkmcnt(0)
	v_add_f32_e32 v205, v205, v206
	ds_bpermute_b32 v206, v204, v205
	s_lshl_b32 s0, s11, 3
	s_add_i32 s2, s0, 0
	s_waitcnt lgkmcnt(0)
	v_add_f32_e32 v205, v205, v206
	v_fmamk_f32 v207, v205, 0xbc800000, v153
	v_fmac_f32_e32 v229, 0xbc800000, v205
	v_fmamk_f32 v206, v205, 0xbc800000, v152
	v_fmamk_f32 v228, v205, 0xbc800000, v150
	v_mul_f32_e32 v229, v229, v229
	v_mul_f32_e32 v207, v207, v207
	v_fmac_f32_e32 v229, v228, v228
	v_fmac_f32_e32 v207, v206, v206
	v_fmamk_f32 v228, v205, 0xbc800000, v149
	v_fmac_f32_e32 v230, 0xbc800000, v205
	v_add_f32_e32 v206, v229, v207
	v_fmamk_f32 v207, v205, 0xbc800000, v148
	v_fmamk_f32 v229, v205, 0xbc800000, v162
	v_mul_f32_e32 v230, v230, v230
	v_mul_f32_e32 v228, v228, v228
	v_fmac_f32_e32 v230, v229, v229
	v_fmac_f32_e32 v228, v207, v207
	v_add_f32_e32 v207, v230, v228
	v_mov_b32_e32 v230, v143
	v_fmamk_f32 v228, v205, 0xbc800000, v145
	v_fmac_f32_e32 v230, 0xbc800000, v205
	v_add_f32_e32 v206, v206, v207
	v_fmamk_f32 v207, v205, 0xbc800000, v144
	v_fmamk_f32 v229, v205, 0xbc800000, v142
	v_mul_f32_e32 v230, v230, v230
	v_mul_f32_e32 v228, v228, v228
	v_fmac_f32_e32 v230, v229, v229
	v_fmac_f32_e32 v228, v207, v207
	v_add_f32_e32 v207, v230, v228
	v_mov_b32_e32 v230, v165
	v_fmamk_f32 v228, v205, 0xbc800000, v141
	v_fmac_f32_e32 v230, 0xbc800000, v205
	v_add_f32_e32 v206, v207, v206
	v_fmamk_f32 v207, v205, 0xbc800000, v140
	v_fmamk_f32 v229, v205, 0xbc800000, v164
	v_mul_f32_e32 v230, v230, v230
	v_mul_f32_e32 v228, v228, v228
	v_fmac_f32_e32 v230, v229, v229
	v_fmac_f32_e32 v228, v207, v207
	v_add_f32_e32 v207, v230, v228
	v_add_f32_e32 v206, v207, v206
	ds_bpermute_b32 v207, v154, v206
	s_waitcnt lgkmcnt(0)
	v_add_f32_e32 v207, v206, v207
	ds_bpermute_b32 v228, v204, v207
	v_and_b32_e32 v206, 63, v227
	v_cmp_gt_u32_e32 vcc, 16, v206
	s_and_saveexec_b64 s[0:1], vcc
	s_cbranch_execz .LBB0_305
	s_lshl_b32 s3, s40, 11
	s_add_i32 s3, s2, s3
	v_mul_f32_e32 v230, 0x3c800000, v205
	v_lshl_add_u32 v205, v1, 5, s3
	s_waitcnt lgkmcnt(0)
	v_add_f32_e32 v231, v207, v228
	ds_write_b64 v205, v[230:231]
